# b8 + cross-half row max via v_permlane32_swap instead of ds_bpermute
# baseline (speedup 1.0000x reference)
.LBB0_1465:
	v_lshrrev_b32_e32 v0, s40, v104
	v_and_b32_e32 v0, 1, v0
	v_cmp_eq_u32_e32 vcc, 1, v0
	s_or_b64 s[0:1], s[0:1], vcc
	v_cndmask_b32_e64 v0, v211, v129, s[0:1]
	v_add_u32_e32 v252, s37, v204
	ds_read_b64_tr_b16 v[236:237], v252 offset:18432
	ds_read_b64_tr_b16 v[238:239], v252 offset:19584
	ds_read_b64_tr_b16 v[240:241], v252 offset:18496
	ds_read_b64_tr_b16 v[242:243], v252 offset:19648
	ds_read_b64_tr_b16 v[244:245], v252 offset:20736
	ds_read_b64_tr_b16 v[246:247], v252 offset:21888
	ds_read_b64_tr_b16 v[248:249], v252 offset:20800
	ds_read_b64_tr_b16 v[250:251], v252 offset:21952
	s_mov_b64 s[2:3], -1
	v_mov_b32_e32 v1, v0
	v_mov_b32_e32 v2, v0
	s_nop 1
	v_permlane32_swap_b32_e32 v1, v2
	v_max3_f32 v33, v123, v1, v2
	v_cmp_neq_f32_e32 vcc, s70, v33
	s_nop 1
	v_cndmask_b32_e32 v125, 0, v33, vcc
	v_cndmask_b32_e64 v253, v212, v125, s[0:1]
	v_sub_f32_e32 v0, v38, v253
	v_sub_f32_e32 v1, v39, v253
	v_sub_f32_e32 v2, v36, v253
	v_sub_f32_e32 v3, v37, v253
	v_sub_f32_e32 v4, v40, v253
	v_sub_f32_e32 v5, v41, v253
	v_sub_f32_e32 v6, v34, v253
	v_sub_f32_e32 v7, v35, v253
	v_sub_f32_e32 v8, v134, v253
	v_sub_f32_e32 v9, v135, v253
	v_sub_f32_e32 v10, v44, v253
	v_sub_f32_e32 v11, v45, v253
	v_sub_f32_e32 v12, v46, v253
	v_sub_f32_e32 v13, v47, v253
	v_sub_f32_e32 v14, v42, v253
	v_sub_f32_e32 v15, v43, v253
	v_sub_f32_e32 v16, v142, v253
	v_sub_f32_e32 v17, v143, v253
	v_sub_f32_e32 v18, v138, v253
	v_sub_f32_e32 v19, v139, v253
	v_sub_f32_e32 v20, v140, v253
	v_sub_f32_e32 v21, v141, v253
	v_sub_f32_e32 v22, v136, v253
	v_sub_f32_e32 v23, v137, v253
	v_sub_f32_e32 v24, v150, v253
	v_sub_f32_e32 v25, v151, v253
	v_sub_f32_e32 v26, v146, v253
	v_sub_f32_e32 v27, v147, v253
	v_sub_f32_e32 v28, v148, v253
	v_sub_f32_e32 v29, v149, v253
	v_sub_f32_e32 v30, v144, v253
	v_sub_f32_e32 v31, v145, v253
	v_sub_f32_e32 v34, v123, v125
	v_exp_f32_e32 v34, v34
	s_waitcnt lgkmcnt(6)
	ds_read_b64_tr_b16 v[134:135], v252 offset:23040
	ds_read_b64_tr_b16 v[136:137], v252 offset:24192
	ds_read_b64_tr_b16 v[138:139], v252 offset:23104
	ds_read_b64_tr_b16 v[140:141], v252 offset:24256
	ds_read_b64_tr_b16 v[142:143], v252 offset:25344
	ds_read_b64_tr_b16 v[144:145], v252 offset:26496
	ds_read_b64_tr_b16 v[146:147], v252 offset:25408
	ds_read_b64_tr_b16 v[148:149], v252 offset:26560
	v_cmp_neq_f32_e32 vcc, 1.0, v34
	v_mov_b32_e32 v37, 0
	s_cbranch_vccz .Lfa_norescale2
	v_pk_mul_f32 v[78:79], v[78:79], v[34:35] op_sel_hi:[1,0]
	v_pk_mul_f32 v[76:77], v[76:77], v[34:35] op_sel_hi:[1,0]
	v_pk_mul_f32 v[74:75], v[74:75], v[34:35] op_sel_hi:[1,0]
	v_pk_mul_f32 v[72:73], v[72:73], v[34:35] op_sel_hi:[1,0]
	v_pk_mul_f32 v[70:71], v[70:71], v[34:35] op_sel_hi:[1,0]
	v_pk_mul_f32 v[68:69], v[68:69], v[34:35] op_sel_hi:[1,0]
	v_pk_mul_f32 v[66:67], v[66:67], v[34:35] op_sel_hi:[1,0]
	v_pk_mul_f32 v[64:65], v[64:65], v[34:35] op_sel_hi:[1,0]
	v_pk_mul_f32 v[62:63], v[62:63], v[34:35] op_sel_hi:[1,0]
	v_pk_mul_f32 v[60:61], v[60:61], v[34:35] op_sel_hi:[1,0]
	v_pk_mul_f32 v[58:59], v[58:59], v[34:35] op_sel_hi:[1,0]
	v_pk_mul_f32 v[56:57], v[56:57], v[34:35] op_sel_hi:[1,0]
	v_pk_mul_f32 v[54:55], v[54:55], v[34:35] op_sel_hi:[1,0]
	v_pk_mul_f32 v[52:53], v[52:53], v[34:35] op_sel_hi:[1,0]
	v_pk_mul_f32 v[50:51], v[50:51], v[34:35] op_sel_hi:[1,0]
	v_pk_mul_f32 v[48:49], v[48:49], v[34:35] op_sel_hi:[1,0]

.Lfa_fast:
	v_mov_b32_e32 v33, s69
	ds_read_b32 v127, v33 offset:764
	v_max_f32_e32 v252, v0, v1
	v_max3_f32 v252, v252, v2, v3
	v_max3_f32 v252, v252, v4, v5
	v_max3_f32 v252, v252, v6, v7
	v_max3_f32 v252, v252, v8, v9
	v_max3_f32 v252, v252, v10, v11
	v_max3_f32 v252, v252, v12, v13
	v_max3_f32 v252, v252, v14, v15
	v_max3_f32 v252, v252, v16, v17
	v_max3_f32 v252, v252, v18, v19
	v_max3_f32 v252, v252, v20, v21
	v_max3_f32 v252, v252, v22, v23
	v_max3_f32 v252, v252, v24, v25
	v_max3_f32 v252, v252, v26, v27
	v_max3_f32 v252, v252, v28, v29
	v_max3_f32 v252, v252, v30, v31
	v_lshrrev_b32_e32 v253, s40, v104
	v_and_b32_e32 v253, 1, v253
	v_cmp_eq_u32_e32 vcc, 1, v253
	s_or_b64 s[0:1], s[0:1], vcc
	s_waitcnt lgkmcnt(0)
	v_fmamk_f32 v129, v252, 0x3fb8aa3b, v127
	v_cndmask_b32_e64 v252, v211, v129, s[0:1]
	v_add_u32_e32 v47, s37, v204
	ds_read_b64_tr_b16 v[134:135], v47 offset:18432
	ds_read_b64_tr_b16 v[136:137], v47 offset:19584
	ds_read_b64_tr_b16 v[138:139], v47 offset:18496
	ds_read_b64_tr_b16 v[140:141], v47 offset:19648
	ds_read_b64_tr_b16 v[142:143], v47 offset:20736
	ds_read_b64_tr_b16 v[144:145], v47 offset:21888
	ds_read_b64_tr_b16 v[146:147], v47 offset:20800
	ds_read_b64_tr_b16 v[148:149], v47 offset:21952
	v_mov_b32_e32 v253, v252
	v_mov_b32_e32 v38, v252
	s_nop 1
	v_permlane32_swap_b32_e32 v253, v38
	v_max3_f32 v33, v123, v253, v38
	v_cmp_neq_f32_e32 vcc, s70, v33
	s_nop 1
	v_cndmask_b32_e32 v125, 0, v33, vcc
	v_sub_f32_e32 v252, v127, v125
	v_cndmask_b32_e64 v36, v211, v252, s[0:1]
	v_sub_f32_e32 v34, v123, v125
	v_exp_f32_e32 v34, v34
	s_waitcnt lgkmcnt(6)
	ds_read_b64_tr_b16 v[236:237], v47 offset:23040
	ds_read_b64_tr_b16 v[238:239], v47 offset:24192
	ds_read_b64_tr_b16 v[240:241], v47 offset:23104
	ds_read_b64_tr_b16 v[242:243], v47 offset:24256
	ds_read_b64_tr_b16 v[244:245], v47 offset:25344
	ds_read_b64_tr_b16 v[246:247], v47 offset:26496
	ds_read_b64_tr_b16 v[248:249], v47 offset:25408
	ds_read_b64_tr_b16 v[250:251], v47 offset:26560
	v_cmp_neq_f32_e32 vcc, 1.0, v34
	v_mov_b32_e32 v37, 0
	s_cbranch_vccz .Lfa_norescale
	v_pk_mul_f32 v[78:79], v[78:79], v[34:35] op_sel_hi:[1,0]
	v_pk_mul_f32 v[76:77], v[76:77], v[34:35] op_sel_hi:[1,0]
	v_pk_mul_f32 v[74:75], v[74:75], v[34:35] op_sel_hi:[1,0]
	v_pk_mul_f32 v[72:73], v[72:73], v[34:35] op_sel_hi:[1,0]
	v_pk_mul_f32 v[70:71], v[70:71], v[34:35] op_sel_hi:[1,0]
	v_pk_mul_f32 v[68:69], v[68:69], v[34:35] op_sel_hi:[1,0]
	v_pk_mul_f32 v[66:67], v[66:67], v[34:35] op_sel_hi:[1,0]
	v_pk_mul_f32 v[64:65], v[64:65], v[34:35] op_sel_hi:[1,0]
	v_pk_mul_f32 v[62:63], v[62:63], v[34:35] op_sel_hi:[1,0]
	v_pk_mul_f32 v[60:61], v[60:61], v[34:35] op_sel_hi:[1,0]
	v_pk_mul_f32 v[58:59], v[58:59], v[34:35] op_sel_hi:[1,0]
	v_pk_mul_f32 v[56:57], v[56:57], v[34:35] op_sel_hi:[1,0]
	v_pk_mul_f32 v[54:55], v[54:55], v[34:35] op_sel_hi:[1,0]
	v_pk_mul_f32 v[52:53], v[52:53], v[34:35] op_sel_hi:[1,0]
	v_pk_mul_f32 v[50:51], v[50:51], v[34:35] op_sel_hi:[1,0]
	v_pk_mul_f32 v[48:49], v[48:49], v[34:35] op_sel_hi:[1,0]
